# per-unit static priority: waves 4-7 at s_setprio 1 during retention and sample units (prompt attention keeps its loop-level raise)
# baseline (speedup 1.0000x reference)
; DI void p2_units(const Params& p, LAS unsigned char* lds, int dup) {
;     ...
;     for (;;) {
;         __syncthreads();
;         if (tid == 0) *qslot = (int)atomicAdd(ctr, 1u);
;         __syncthreads();
;         int u = *qslot;
;         if (u >= NU_TOTAL) break;
;         if (u < NU_R1) { const int bhp = u / 7, seg = u - bhp * 7; ret_unit(p, lds, 0, bhp >> 1, bhp & 1, seg); continue; }
;         u -= NU_R1;
;         int kind = 0, bh, uu = 0;
;         if (u < NU_AS) { kind = 1; bh = u; }
;         else if (u < NU_AS + NU_A1) { const int a = u - NU_AS; bh = a & 63; uu = 31 - (a >> 6); }
;         else if (u < NU_AS + NU_A1 + NU_R2) { const int rr = u - NU_AS - NU_A1; ret_unit(p, lds, 1, (rr & 31) >> 1, rr & 1, rr >> 5); continue; }
;         else if (u < NU_AS + NU_A1 + NU_R2 + NU_A2) { const int a = u - NU_AS - NU_R2; bh = a & 63; uu = 31 - (a >> 6); }
;         else { const int rr = u - NU_AS - NU_A1 - NU_R2 - NU_A2; ret_unit(p, lds, 2, rr >> 1, rr & 1, 0); continue; }
;         attn_unit(p, lds, kind, bh >> 2, bh & 3, uu, lam);
.Lq_done:
	s_setprio 0
	v_readfirstlane_b32 s98, v182
	s_nop 0
	s_cmpk_lt_u32 s98, 0x100
	s_cbranch_scc1 .Lprio_u_done
	s_cmpk_lt_u32 s94, 0x120
	s_cbranch_scc1 .Lprio_u_hi
	s_cmpk_lt_u32 s94, 0x220
	s_cbranch_scc1 .Lprio_u_done
	s_cmpk_lt_u32 s94, 0x320
	s_cbranch_scc1 .Lprio_u_hi
	s_cmpk_lt_u32 s94, 0xa20
	s_cbranch_scc1 .Lprio_u_done
.Lprio_u_hi:
	s_setprio 1
